# pool-gemm-epilogue-gate-scale-loads-batched
# speedup vs baseline: 1.0007x; 1.0007x over previous
; #define PG8_STAGE(bufoff, gbase, hoff, imm) do { _Pragma("unroll") for (int _i = 0; _i < 2; ++_i) { \
;         asm volatile("s_mov_b32 m0, %0\n\ts_nop 0\n\tglobal_load_lds_dwordx4 %1, %2" \
;             :: "s"(lds0 + (unsigned)((bufoff) + _i * 8192)), "v"(voff0), "s"((const char*)(gbase) + (size_t)(hoff) + (size_t)(_i * 8192)) : "memory"); } } while (0)
; #define PG8_LDA(dst, b, h) do { _Pragma("unroll") for (int m = 0; m < 4; ++m) _Pragma("unroll") for (int k = 0; k < 2; ++k) dst[m][k] = *(const LAS bf16x8*)(lds + PG8_SA(b, h) + aoff + m * 2048 + k * 1024); } while (0)
; #define PG8_LDB(dst, b, h) do { _Pragma("unroll") for (int n = 0; n < 2; ++n) _Pragma("unroll") for (int k = 0; k < 2; ++k) dst[n][k] = *(const LAS bf16x8*)(lds + PG8_SB(b, h) + boff + n * 2048 + k * 1024); } while (0)
; #define PG8_MMA(ai, bj, At, Bt) do { __builtin_amdgcn_s_setprio(1); _Pragma("unroll") for (int m = 0; m < 4; ++m) _Pragma("unroll") for (int n = 0; n < 2; ++n) _Pragma("unroll") for (int k = 0; k < 2; ++k) \
;         acc[ai][bj][m][n] = __builtin_amdgcn_mfma_f32_16x16x32_bf16(Bt[n][k], At[m][k], acc[ai][bj][m][n], 0, 0, 0); __builtin_amdgcn_s_setprio(0); } while (0)
; #define PG8_WAIT_L(n) asm volatile("s_waitcnt lgkmcnt(" #n ")" ::: "memory")
; #define PG8_BAR __builtin_amdgcn_s_barrier()
; #define PG8_SCHED __builtin_amdgcn_sched_barrier(0)
; template <class Epi>
; __device__ __forceinline__ void gemm_phase(LAS unsigned char* lds, const Gemm g, const StaticOrder& S, const Epi& E) {
;     ...
;             const char* aT = cA + (size_t)t * KS;
;             const char* a2 = last ? nA : aT + 2 * KS; const char* b2 = last ? nB : cB + (size_t)(t + 2) * KS;
;             PG8_LDB(B0, 0, 0); PG8_SCHED; PG8_LDA(At, 0, 0); PG8_STAGE(PG8_SA(1, 1), aT + KS, hA, 0);
;             PG8_WAIT_L(8); PG8_BAR; PG8_WAIT_L(0); PG8_MMA(0, 0, At, B0); PG8_BAR; PG8_SCHED;
;             PG8_LDB(B1, 0, 1); PG8_STAGE(PG8_SB(0, 0), b2, 0, 0);
;             PG8_BAR; PG8_WAIT_L(0); PG8_MMA(0, 1, At, B1); PG8_BAR;
;             PG8_LDA(At, 0, 1); PG8_STAGE(PG8_SA(0, 0), a2, 0, 0);
;             PG8_BAR; PG8_WAIT_L(0); PG8_MMA(1, 0, At, B0); PG8_BAR; PG8_SCHED;
.LBB0_293:
	s_add_u32 s52, s8, 0x8000
	s_addc_u32 s53, s9, 0
	ds_read_b128 v[128:131], v224
	ds_read_b128 v[132:135], v224 offset:1024
	ds_read_b128 v[136:139], v224 offset:2048
	ds_read_b128 v[140:143], v224 offset:3072
	s_add_u32 s54, s8, 0x84000
	s_addc_u32 s55, s9, 0
	s_add_u32 s96, s8, 0x86000
	s_addc_u32 s97, s9, 0
	s_cmp_eq_u32 s95, 4
	s_cselect_b32 s9, s0, s53
	s_cselect_b32 s8, s1, s52
	ds_read_b128 v[144:147], v225
	ds_read_b128 v[148:151], v225 offset:1024
	ds_read_b128 v[152:155], v225 offset:2048
	ds_read_b128 v[156:159], v225 offset:3072
	ds_read_b128 v[160:163], v225 offset:4096
	ds_read_b128 v[164:167], v225 offset:5120
	ds_read_b128 v[168:171], v225 offset:6144
	ds_read_b128 v[172:175], v225 offset:7168
	s_mov_b32 m0, s86
	s_nop 0
	global_load_lds_dwordx4 v221, s[54:55]
	s_mov_b32 m0, s87
	s_nop 0
	global_load_lds_dwordx4 v221, s[96:97]
	s_waitcnt lgkmcnt(8)
	s_waitcnt vmcnt(10)
	s_barrier
	s_waitcnt lgkmcnt(0)
	s_waitcnt lgkmcnt(7)
	v_mfma_f32_16x16x32_bf16 v[124:127], v[128:131], v[144:147], v[124:127]
	v_mfma_f32_16x16x32_bf16 v[120:123], v[136:139], v[144:147], v[120:123]
	s_waitcnt lgkmcnt(5)
	v_mfma_f32_16x16x32_bf16 v[116:119], v[128:131], v[152:155], v[116:119]
	v_mfma_f32_16x16x32_bf16 v[112:115], v[136:139], v[152:155], v[112:115]
	s_waitcnt lgkmcnt(3)
	v_mfma_f32_16x16x32_bf16 v[96:99], v[128:131], v[160:163], v[96:99]
	v_mfma_f32_16x16x32_bf16 v[88:91], v[136:139], v[160:163], v[88:91]
	s_waitcnt lgkmcnt(1)
	v_mfma_f32_16x16x32_bf16 v[80:83], v[128:131], v[168:171], v[80:83]
	v_mfma_f32_16x16x32_bf16 v[72:75], v[136:139], v[168:171], v[72:75]
	v_mfma_f32_16x16x32_bf16 v[124:127], v[132:135], v[148:151], v[124:127]
	v_mfma_f32_16x16x32_bf16 v[120:123], v[140:143], v[148:151], v[120:123]
	v_mfma_f32_16x16x32_bf16 v[116:119], v[132:135], v[156:159], v[116:119]
	v_mfma_f32_16x16x32_bf16 v[112:115], v[140:143], v[156:159], v[112:115]
	v_mfma_f32_16x16x32_bf16 v[96:99], v[132:135], v[164:167], v[96:99]
	v_mfma_f32_16x16x32_bf16 v[88:91], v[140:143], v[164:167], v[88:91]
	s_waitcnt lgkmcnt(0)
	v_mfma_f32_16x16x32_bf16 v[80:83], v[132:135], v[172:175], v[80:83]
	v_mfma_f32_16x16x32_bf16 v[72:75], v[140:143], v[172:175], v[72:75]
	s_barrier
	ds_read_b128 v[176:179], v226
	ds_read_b128 v[180:183], v226 offset:1024
	ds_read_b128 v[184:187], v226 offset:2048
	ds_read_b128 v[188:191], v226 offset:3072
	s_cselect_b32 s54, s47, s93
	s_cselect_b32 s55, s45, s94
	s_mov_b32 m0, s60
	s_nop 0
	global_load_lds_dwordx4 v221, s[54:55]
	s_add_u32 s96, s54, 0x2000
	s_addc_u32 s97, s55, 0
	s_mov_b32 m0, s61
	s_nop 0
	global_load_lds_dwordx4 v221, s[96:97]
	s_waitcnt vmcnt(10)
	s_barrier
	s_waitcnt lgkmcnt(0)
	s_waitcnt lgkmcnt(3)
	v_mfma_f32_16x16x32_bf16 v[108:111], v[176:179], v[144:147], v[108:111]
	s_waitcnt lgkmcnt(1)
	v_mfma_f32_16x16x32_bf16 v[104:107], v[184:187], v[144:147], v[104:107]
	v_mfma_f32_16x16x32_bf16 v[100:103], v[176:179], v[152:155], v[100:103]
	v_mfma_f32_16x16x32_bf16 v[92:95], v[184:187], v[152:155], v[92:95]
	v_mfma_f32_16x16x32_bf16 v[84:87], v[176:179], v[160:163], v[84:87]
	v_mfma_f32_16x16x32_bf16 v[76:79], v[184:187], v[160:163], v[76:79]
	v_mfma_f32_16x16x32_bf16 v[68:71], v[176:179], v[168:171], v[68:71]
	v_mfma_f32_16x16x32_bf16 v[64:67], v[184:187], v[168:171], v[64:67]
	v_mfma_f32_16x16x32_bf16 v[108:111], v[180:183], v[148:151], v[108:111]
	s_waitcnt lgkmcnt(0)
	v_mfma_f32_16x16x32_bf16 v[104:107], v[188:191], v[148:151], v[104:107]
	v_mfma_f32_16x16x32_bf16 v[100:103], v[180:183], v[156:159], v[100:103]
	v_mfma_f32_16x16x32_bf16 v[92:95], v[188:191], v[156:159], v[92:95]
	v_mfma_f32_16x16x32_bf16 v[84:87], v[180:183], v[164:167], v[84:87]
	v_mfma_f32_16x16x32_bf16 v[76:79], v[188:191], v[164:167], v[76:79]
	v_mfma_f32_16x16x32_bf16 v[68:71], v[180:183], v[172:175], v[68:71]
	v_mfma_f32_16x16x32_bf16 v[64:67], v[188:191], v[172:175], v[64:67]
	s_barrier
	ds_read_b128 v[144:147], v225 offset:16384
	ds_read_b128 v[148:151], v225 offset:17408
	ds_read_b128 v[152:155], v225 offset:18432
	ds_read_b128 v[156:159], v225 offset:19456
	ds_read_b128 v[160:163], v225 offset:20480
	ds_read_b128 v[164:167], v225 offset:21504
	ds_read_b128 v[168:171], v225 offset:22528
	ds_read_b128 v[172:175], v225 offset:23552
	s_mov_b32 m0, s59
	s_nop 0
	global_load_lds_dwordx4 v221, s[8:9]
	s_add_u32 s96, s8, 0x2000
	s_addc_u32 s97, s9, 0
	s_mov_b32 m0, s62
	s_nop 0
	global_load_lds_dwordx4 v221, s[96:97]
	s_barrier
	s_waitcnt lgkmcnt(0)
	s_waitcnt lgkmcnt(7)
	v_mfma_f32_16x16x32_bf16 v[60:63], v[128:131], v[144:147], v[60:63]
	v_mfma_f32_16x16x32_bf16 v[56:59], v[136:139], v[144:147], v[56:59]
	s_waitcnt lgkmcnt(5)
	v_mfma_f32_16x16x32_bf16 v[48:51], v[128:131], v[152:155], v[48:51]
	v_mfma_f32_16x16x32_bf16 v[40:43], v[136:139], v[152:155], v[40:43]
	s_waitcnt lgkmcnt(3)
	v_mfma_f32_16x16x32_bf16 v[32:35], v[128:131], v[160:163], v[32:35]
	v_mfma_f32_16x16x32_bf16 v[24:27], v[136:139], v[160:163], v[24:27]
	s_waitcnt lgkmcnt(1)
	v_mfma_f32_16x16x32_bf16 v[16:19], v[128:131], v[168:171], v[16:19]
	v_mfma_f32_16x16x32_bf16 v[8:11], v[136:139], v[168:171], v[8:11]
	v_mfma_f32_16x16x32_bf16 v[60:63], v[132:135], v[148:151], v[60:63]
	v_mfma_f32_16x16x32_bf16 v[56:59], v[140:143], v[148:151], v[56:59]
	v_mfma_f32_16x16x32_bf16 v[48:51], v[132:135], v[156:159], v[48:51]
	v_mfma_f32_16x16x32_bf16 v[40:43], v[140:143], v[156:159], v[40:43]
	v_mfma_f32_16x16x32_bf16 v[32:35], v[132:135], v[164:167], v[32:35]
	v_mfma_f32_16x16x32_bf16 v[24:27], v[140:143], v[164:167], v[24:27]
	s_waitcnt lgkmcnt(0)
	v_mfma_f32_16x16x32_bf16 v[16:19], v[132:135], v[172:175], v[16:19]
	v_mfma_f32_16x16x32_bf16 v[8:11], v[140:143], v[172:175], v[8:11]
	s_barrier
; #define PG8_STAGE(bufoff, gbase, hoff, imm) do { _Pragma("unroll") for (int _i = 0; _i < 2; ++_i) { \
;         asm volatile("s_mov_b32 m0, %0\n\ts_nop 0\n\tglobal_load_lds_dwordx4 %1, %2" \
;             :: "s"(lds0 + (unsigned)((bufoff) + _i * 8192)), "v"(voff0), "s"((const char*)(gbase) + (size_t)(hoff) + (size_t)(_i * 8192)) : "memory"); } } while (0)
; #define PG8_LDA(dst, b, h) do { _Pragma("unroll") for (int m = 0; m < 4; ++m) _Pragma("unroll") for (int k = 0; k < 2; ++k) dst[m][k] = *(const LAS bf16x8*)(lds + PG8_SA(b, h) + aoff + m * 2048 + k * 1024); } while (0)
; #define PG8_LDB(dst, b, h) do { _Pragma("unroll") for (int n = 0; n < 2; ++n) _Pragma("unroll") for (int k = 0; k < 2; ++k) dst[n][k] = *(const LAS bf16x8*)(lds + PG8_SB(b, h) + boff + n * 2048 + k * 1024); } while (0)
; #define PG8_MMA(ai, bj, At, Bt) do { __builtin_amdgcn_s_setprio(1); _Pragma("unroll") for (int m = 0; m < 4; ++m) _Pragma("unroll") for (int n = 0; n < 2; ++n) _Pragma("unroll") for (int k = 0; k < 2; ++k) \
;         acc[ai][bj][m][n] = __builtin_amdgcn_mfma_f32_16x16x32_bf16(Bt[n][k], At[m][k], acc[ai][bj][m][n], 0, 0, 0); __builtin_amdgcn_s_setprio(0); } while (0)
; #define PG8_WAIT_V(n) asm volatile("s_waitcnt vmcnt(" #n ")" ::: "memory")
; #define PG8_WAIT_L(n) asm volatile("s_waitcnt lgkmcnt(" #n ")" ::: "memory")
; #define PG8_BAR __builtin_amdgcn_s_barrier()
; #define PG8_SCHED __builtin_amdgcn_sched_barrier(0)
; template <class Epi>
; __device__ __forceinline__ void gemm_phase(LAS unsigned char* lds, const Gemm g, const StaticOrder& S, const Epi& E) {
;     ...
;             PG8_STAGE(PG8_SB(0, 1), b2, hB, 0);
;             PG8_WAIT_V(6); PG8_BAR; PG8_MMA(1, 1, At, B1); PG8_BAR;
;             PG8_LDB(B0, 1, 0); PG8_SCHED; PG8_LDA(At, 1, 0); PG8_STAGE(PG8_SA(0, 1), a2, hA, 0);
;             PG8_WAIT_L(8); PG8_BAR; PG8_WAIT_L(0); PG8_MMA(0, 0, At, B0); PG8_BAR; PG8_SCHED;
;             PG8_LDB(B1, 1, 1); PG8_STAGE(PG8_SB(1, 0), b2 + KS, 0, 0);
;             PG8_BAR; PG8_WAIT_L(0); PG8_MMA(0, 1, At, B1); PG8_BAR;
;             PG8_LDA(At, 1, 1); PG8_STAGE(PG8_SA(1, 0), a2 + KS, 0, 0);
	s_add_u32 s96, s54, 0x20000
	s_addc_u32 s97, s55, 0
	s_mov_b32 m0, s63
	s_nop 0
	global_load_lds_dwordx4 v221, s[96:97]
	s_add_u32 s96, s54, 0x22000
	s_addc_u32 s97, s55, 0
	s_mov_b32 m0, s64
	s_nop 0
	global_load_lds_dwordx4 v221, s[96:97]
	s_waitcnt vmcnt(10)
	s_barrier
	v_mfma_f32_16x16x32_bf16 v[52:55], v[176:179], v[144:147], v[52:55]
	v_mfma_f32_16x16x32_bf16 v[44:47], v[184:187], v[144:147], v[44:47]
	v_mfma_f32_16x16x32_bf16 v[36:39], v[176:179], v[152:155], v[36:39]
	v_mfma_f32_16x16x32_bf16 v[28:31], v[184:187], v[152:155], v[28:31]
	v_mfma_f32_16x16x32_bf16 v[20:23], v[176:179], v[160:163], v[20:23]
	v_mfma_f32_16x16x32_bf16 v[12:15], v[184:187], v[160:163], v[12:15]
	v_mfma_f32_16x16x32_bf16 v[4:7], v[176:179], v[168:171], v[4:7]
	v_mfma_f32_16x16x32_bf16 v[0:3], v[184:187], v[168:171], v[0:3]
	v_mfma_f32_16x16x32_bf16 v[52:55], v[180:183], v[148:151], v[52:55]
	v_mfma_f32_16x16x32_bf16 v[44:47], v[188:191], v[148:151], v[44:47]
	v_mfma_f32_16x16x32_bf16 v[36:39], v[180:183], v[156:159], v[36:39]
	v_mfma_f32_16x16x32_bf16 v[28:31], v[188:191], v[156:159], v[28:31]
	v_mfma_f32_16x16x32_bf16 v[20:23], v[180:183], v[164:167], v[20:23]
	v_mfma_f32_16x16x32_bf16 v[12:15], v[188:191], v[164:167], v[12:15]
	v_mfma_f32_16x16x32_bf16 v[4:7], v[180:183], v[172:175], v[4:7]
	v_mfma_f32_16x16x32_bf16 v[0:3], v[188:191], v[172:175], v[0:3]
	s_barrier
	ds_read_b128 v[128:131], v227
	ds_read_b128 v[132:135], v227 offset:1024
	ds_read_b128 v[136:139], v227 offset:2048
	ds_read_b128 v[140:143], v227 offset:3072
	ds_read_b128 v[144:147], v225 offset:32768
	ds_read_b128 v[148:151], v225 offset:33792
	ds_read_b128 v[152:155], v225 offset:34816
	ds_read_b128 v[156:159], v225 offset:35840
	ds_read_b128 v[160:163], v225 offset:36864
	ds_read_b128 v[164:167], v225 offset:37888
	ds_read_b128 v[168:171], v225 offset:38912
	ds_read_b128 v[172:175], v225 offset:39936
	s_add_u32 s96, s8, 0x80000
	s_addc_u32 s97, s9, 0
	s_mov_b32 m0, s65
	s_nop 0
	global_load_lds_dwordx4 v221, s[96:97]
	s_add_u32 s96, s8, 0x82000
	s_addc_u32 s97, s9, 0
	s_mov_b32 m0, s66
	s_nop 0
	global_load_lds_dwordx4 v221, s[96:97]
	s_waitcnt lgkmcnt(8)
	s_waitcnt vmcnt(10)
	s_barrier
	s_waitcnt lgkmcnt(0)
	s_waitcnt lgkmcnt(7)
	v_mfma_f32_16x16x32_bf16 v[124:127], v[128:131], v[144:147], v[124:127]
	v_mfma_f32_16x16x32_bf16 v[120:123], v[136:139], v[144:147], v[120:123]
	s_waitcnt lgkmcnt(5)
	v_mfma_f32_16x16x32_bf16 v[116:119], v[128:131], v[152:155], v[116:119]
	v_mfma_f32_16x16x32_bf16 v[112:115], v[136:139], v[152:155], v[112:115]
	s_waitcnt lgkmcnt(3)
	v_mfma_f32_16x16x32_bf16 v[96:99], v[128:131], v[160:163], v[96:99]
	v_mfma_f32_16x16x32_bf16 v[88:91], v[136:139], v[160:163], v[88:91]
	s_waitcnt lgkmcnt(1)
	v_mfma_f32_16x16x32_bf16 v[80:83], v[128:131], v[168:171], v[80:83]
	v_mfma_f32_16x16x32_bf16 v[72:75], v[136:139], v[168:171], v[72:75]
	v_mfma_f32_16x16x32_bf16 v[124:127], v[132:135], v[148:151], v[124:127]
	v_mfma_f32_16x16x32_bf16 v[120:123], v[140:143], v[148:151], v[120:123]
	v_mfma_f32_16x16x32_bf16 v[116:119], v[132:135], v[156:159], v[116:119]
	v_mfma_f32_16x16x32_bf16 v[112:115], v[140:143], v[156:159], v[112:115]
	v_mfma_f32_16x16x32_bf16 v[96:99], v[132:135], v[164:167], v[96:99]
	v_mfma_f32_16x16x32_bf16 v[88:91], v[140:143], v[164:167], v[88:91]
	s_waitcnt lgkmcnt(0)
	v_mfma_f32_16x16x32_bf16 v[80:83], v[132:135], v[172:175], v[80:83]
	v_mfma_f32_16x16x32_bf16 v[72:75], v[140:143], v[172:175], v[72:75]
	s_barrier
	ds_read_b128 v[176:179], v228
	ds_read_b128 v[180:183], v228 offset:1024
	ds_read_b128 v[184:187], v228 offset:2048
	ds_read_b128 v[188:191], v228 offset:3072
	s_add_u32 s96, s54, 0x4000
	s_addc_u32 s97, s55, 0
	s_mov_b32 m0, s69
	s_nop 0
	global_load_lds_dwordx4 v221, s[96:97]
	s_add_u32 s96, s54, 0x6000
	s_addc_u32 s97, s55, 0
	s_mov_b32 m0, s70
	s_nop 0
	global_load_lds_dwordx4 v221, s[96:97]
	s_waitcnt vmcnt(10)
	s_barrier
	s_waitcnt lgkmcnt(0)
	s_waitcnt lgkmcnt(3)
	v_mfma_f32_16x16x32_bf16 v[108:111], v[176:179], v[144:147], v[108:111]
	s_waitcnt lgkmcnt(1)
	v_mfma_f32_16x16x32_bf16 v[104:107], v[184:187], v[144:147], v[104:107]
	v_mfma_f32_16x16x32_bf16 v[100:103], v[176:179], v[152:155], v[100:103]
	v_mfma_f32_16x16x32_bf16 v[92:95], v[184:187], v[152:155], v[92:95]
	v_mfma_f32_16x16x32_bf16 v[84:87], v[176:179], v[160:163], v[84:87]
	v_mfma_f32_16x16x32_bf16 v[76:79], v[184:187], v[160:163], v[76:79]
	v_mfma_f32_16x16x32_bf16 v[68:71], v[176:179], v[168:171], v[68:71]
	v_mfma_f32_16x16x32_bf16 v[64:67], v[184:187], v[168:171], v[64:67]
	v_mfma_f32_16x16x32_bf16 v[108:111], v[180:183], v[148:151], v[108:111]
	s_waitcnt lgkmcnt(0)
	v_mfma_f32_16x16x32_bf16 v[104:107], v[188:191], v[148:151], v[104:107]
	v_mfma_f32_16x16x32_bf16 v[100:103], v[180:183], v[156:159], v[100:103]
	v_mfma_f32_16x16x32_bf16 v[92:95], v[188:191], v[156:159], v[92:95]
	v_mfma_f32_16x16x32_bf16 v[84:87], v[180:183], v[164:167], v[84:87]
	v_mfma_f32_16x16x32_bf16 v[76:79], v[188:191], v[164:167], v[76:79]
	v_mfma_f32_16x16x32_bf16 v[68:71], v[180:183], v[172:175], v[68:71]
	v_mfma_f32_16x16x32_bf16 v[64:67], v[188:191], v[172:175], v[64:67]
	s_barrier
; #define PG8_STAGE(bufoff, gbase, hoff, imm) do { _Pragma("unroll") for (int _i = 0; _i < 2; ++_i) { \
;         asm volatile("s_mov_b32 m0, %0\n\ts_nop 0\n\tglobal_load_lds_dwordx4 %1, %2" \
;             :: "s"(lds0 + (unsigned)((bufoff) + _i * 8192)), "v"(voff0), "s"((const char*)(gbase) + (size_t)(hoff) + (size_t)(_i * 8192)) : "memory"); } } while (0)
; #define PG8_MMA(ai, bj, At, Bt) do { __builtin_amdgcn_s_setprio(1); _Pragma("unroll") for (int m = 0; m < 4; ++m) _Pragma("unroll") for (int n = 0; n < 2; ++n) _Pragma("unroll") for (int k = 0; k < 2; ++k) \
;         acc[ai][bj][m][n] = __builtin_amdgcn_mfma_f32_16x16x32_bf16(Bt[n][k], At[m][k], acc[ai][bj][m][n], 0, 0, 0); __builtin_amdgcn_s_setprio(0); } while (0)
; #define PG8_WAIT_V(n) asm volatile("s_waitcnt vmcnt(" #n ")" ::: "memory")
; #define PG8_WAIT_L(n) asm volatile("s_waitcnt lgkmcnt(" #n ")" ::: "memory")
; #define PG8_BAR __builtin_amdgcn_s_barrier()
; #define PG8_SCHED __builtin_amdgcn_sched_barrier(0)
; template <class Epi>
; __device__ __forceinline__ void gemm_phase(LAS unsigned char* lds, const Gemm g, const StaticOrder& S, const Epi& E) {
;     ...
;             PG8_BAR; PG8_WAIT_L(0); PG8_MMA(1, 0, At, B0); PG8_BAR; PG8_SCHED;
;             PG8_STAGE(PG8_SB(1, 1), b2 + KS, hB, 0);
;             PG8_WAIT_V(6); PG8_BAR; PG8_MMA(1, 1, At, B1); PG8_BAR;
;     __device__ __forceinline__ void operator()(f32x4 (&acc)[2][2][4][2], const Unit& u, int wr, int wc, int fr, int fq, LAS unsigned char*) const {
;     ...
;         f32x4 sc[2][2];
; #pragma unroll
;         for (int bj = 0; bj < 2; ++bj)
; #pragma unroll
;             for (int n = 0; n < 2; ++n) { f32x4 gt = *(const f32x4*)(gate + (size_t)b * MODW + col0 + bj * HALF + n * 4); sc[bj][n] = gt + 1.0f;
;                 if (cs) sc[bj][n] *= *(const f32x4*)(cs + col0 + bj * HALF + n * 4); }
	ds_read_b128 v[144:147], v225 offset:49152
	ds_read_b128 v[148:151], v225 offset:50176
	ds_read_b128 v[152:155], v225 offset:51200
	ds_read_b128 v[156:159], v225 offset:52224
	ds_read_b128 v[160:163], v225 offset:53248
	ds_read_b128 v[164:167], v225 offset:54272
	ds_read_b128 v[168:171], v225 offset:55296
	ds_read_b128 v[172:175], v225 offset:56320
	s_add_u32 s96, s8, 0x4000
	s_addc_u32 s97, s9, 0
	s_mov_b32 m0, s71
	s_nop 0
	global_load_lds_dwordx4 v221, s[96:97]
	s_add_u32 s8, s8, 0x6000
	s_addc_u32 s9, s9, 0
	s_mov_b32 m0, s72
	s_nop 0
	global_load_lds_dwordx4 v221, s[8:9]
	s_barrier
	s_waitcnt lgkmcnt(0)
	s_waitcnt lgkmcnt(7)
	v_mfma_f32_16x16x32_bf16 v[60:63], v[128:131], v[144:147], v[60:63]
	v_mfma_f32_16x16x32_bf16 v[56:59], v[136:139], v[144:147], v[56:59]
	s_waitcnt lgkmcnt(5)
	v_mfma_f32_16x16x32_bf16 v[48:51], v[128:131], v[152:155], v[48:51]
	v_mfma_f32_16x16x32_bf16 v[40:43], v[136:139], v[152:155], v[40:43]
	s_waitcnt lgkmcnt(3)
	v_mfma_f32_16x16x32_bf16 v[32:35], v[128:131], v[160:163], v[32:35]
	v_mfma_f32_16x16x32_bf16 v[24:27], v[136:139], v[160:163], v[24:27]
	s_waitcnt lgkmcnt(1)
	v_mfma_f32_16x16x32_bf16 v[16:19], v[128:131], v[168:171], v[16:19]
	v_mfma_f32_16x16x32_bf16 v[8:11], v[136:139], v[168:171], v[8:11]
	v_mfma_f32_16x16x32_bf16 v[60:63], v[132:135], v[148:151], v[60:63]
	v_mfma_f32_16x16x32_bf16 v[56:59], v[140:143], v[148:151], v[56:59]
	v_mfma_f32_16x16x32_bf16 v[48:51], v[132:135], v[156:159], v[48:51]
	v_mfma_f32_16x16x32_bf16 v[40:43], v[140:143], v[156:159], v[40:43]
	v_mfma_f32_16x16x32_bf16 v[32:35], v[132:135], v[164:167], v[32:35]
	v_mfma_f32_16x16x32_bf16 v[24:27], v[140:143], v[164:167], v[24:27]
	s_waitcnt lgkmcnt(0)
	v_mfma_f32_16x16x32_bf16 v[16:19], v[132:135], v[172:175], v[16:19]
	v_mfma_f32_16x16x32_bf16 v[8:11], v[140:143], v[172:175], v[8:11]
	s_barrier
	s_add_u32 s8, s54, 0x24000
	s_addc_u32 s9, s55, 0
	s_mov_b32 m0, s73
	s_nop 0
	global_load_lds_dwordx4 v221, s[8:9]
	s_add_u32 s8, s54, 0x26000
	s_addc_u32 s9, s55, 0
	s_mov_b32 m0, s85
	s_nop 0
	global_load_lds_dwordx4 v221, s[8:9]
	s_waitcnt vmcnt(10)
	s_barrier
	v_mfma_f32_16x16x32_bf16 v[52:55], v[176:179], v[144:147], v[52:55]
	v_mfma_f32_16x16x32_bf16 v[44:47], v[184:187], v[144:147], v[44:47]
	v_mfma_f32_16x16x32_bf16 v[36:39], v[176:179], v[152:155], v[36:39]
	v_mfma_f32_16x16x32_bf16 v[28:31], v[184:187], v[152:155], v[28:31]
	v_mfma_f32_16x16x32_bf16 v[20:23], v[176:179], v[160:163], v[20:23]
	v_mfma_f32_16x16x32_bf16 v[12:15], v[184:187], v[160:163], v[12:15]
	v_mfma_f32_16x16x32_bf16 v[4:7], v[176:179], v[168:171], v[4:7]
	v_mfma_f32_16x16x32_bf16 v[0:3], v[184:187], v[168:171], v[0:3]
	v_mfma_f32_16x16x32_bf16 v[52:55], v[180:183], v[148:151], v[52:55]
	v_mfma_f32_16x16x32_bf16 v[44:47], v[188:191], v[148:151], v[44:47]
	v_mfma_f32_16x16x32_bf16 v[36:39], v[180:183], v[156:159], v[36:39]
	v_mfma_f32_16x16x32_bf16 v[28:31], v[188:191], v[156:159], v[28:31]
	v_mfma_f32_16x16x32_bf16 v[20:23], v[180:183], v[164:167], v[20:23]
	v_mfma_f32_16x16x32_bf16 v[12:15], v[188:191], v[164:167], v[12:15]
	v_mfma_f32_16x16x32_bf16 v[4:7], v[180:183], v[172:175], v[4:7]
	v_mfma_f32_16x16x32_bf16 v[0:3], v[188:191], v[172:175], v[0:3]
	s_add_i32 s95, s95, 2
	s_add_u32 s93, s93, 0x8000
	s_addc_u32 s94, s94, 0
	s_cmp_gt_u32 s95, 5
	s_mov_b64 s[8:9], s[52:53]
	s_barrier
	s_cbranch_scc0 .LBB0_293
	s_ashr_i32 s0, s89, 6
	v_lshl_or_b32 v128, s92, 8, v223
	s_mul_hi_i32 s1, s0, 0xc000
	s_mul_i32 s0, s0, 0xc000
	v_ashrrev_i32_e32 v129, 31, v128
	s_add_u32 s0, s67, s0
	s_addc_u32 s1, s68, s1
	v_lshlrev_b64 v[130:131], 2, v[128:129]
	v_lshl_add_u64 v[132:133], s[0:1], 0, v[130:131]
	v_cndmask_b32_e64 v138, 0, 1, s[42:43]
	v_cmp_ne_u32_e64 s[8:9], 1, v138
	v_lshl_add_u64 v[130:131], s[38:39], 0, v[130:131]
	global_load_dwordx4 v[196:199], v[132:133], off
	global_load_dwordx4 v[200:203], v[132:133], off offset:16
	global_load_dwordx4 v[204:207], v[132:133], off offset:512
	global_load_dwordx4 v[208:211], v[132:133], off offset:528
	v_readlane_b32 s96, v255, 3
	v_readlane_b32 s97, v255, 4
	s_andn2_b64 vcc, exec, s[42:43]
	s_cbranch_vccnz .Lp2_nocs
	global_load_dwordx4 v[134:137], v[130:131], off
	global_load_dwordx4 v[138:141], v[130:131], off offset:16
	global_load_dwordx4 v[142:145], v[130:131], off offset:512
	global_load_dwordx4 v[146:149], v[130:131], off offset:528
.Lp2_nocs:
	s_waitcnt vmcnt(0)
	v_pk_add_f32 v[196:197], v[196:197], 1.0 op_sel_hi:[1,0]
	v_pk_add_f32 v[198:199], v[198:199], 1.0 op_sel_hi:[1,0]
	v_pk_add_f32 v[200:201], v[200:201], 1.0 op_sel_hi:[1,0]
	v_pk_add_f32 v[202:203], v[202:203], 1.0 op_sel_hi:[1,0]
	v_pk_add_f32 v[204:205], v[204:205], 1.0 op_sel_hi:[1,0]
	v_pk_add_f32 v[206:207], v[206:207], 1.0 op_sel_hi:[1,0]
	v_pk_add_f32 v[208:209], v[208:209], 1.0 op_sel_hi:[1,0]
	v_pk_add_f32 v[210:211], v[210:211], 1.0 op_sel_hi:[1,0]
	s_andn2_b64 vcc, exec, s[42:43]
	s_cbranch_vccnz .LBB0_285
	v_pk_mul_f32 v[196:197], v[196:197], v[134:135]
	v_pk_mul_f32 v[198:199], v[198:199], v[136:137]
	v_pk_mul_f32 v[200:201], v[200:201], v[138:139]
	v_pk_mul_f32 v[202:203], v[202:203], v[140:141]
	v_pk_mul_f32 v[204:205], v[204:205], v[142:143]
	v_pk_mul_f32 v[206:207], v[206:207], v[144:145]
	v_pk_mul_f32 v[208:209], v[208:209], v[146:147]
	v_pk_mul_f32 v[210:211], v[210:211], v[148:149]
	s_branch .LBB0_285
